# tile-boundary stagger in P1/P10 swiglu GEMMs: keep wave groups one barrier apart across tiles (on top of attn fast loop + p0rows)
# baseline (speedup 1.0000x reference)
.LBB0_128:
	ds_read_b128 v[144:147], v151
	ds_read_b128 v[154:157], v151 offset:1024
	ds_read_b128 v[158:161], v151 offset:2048
	ds_read_b128 v[162:165], v151 offset:3072
	ds_read_b128 v[166:169], v152
	ds_read_b128 v[170:173], v152 offset:1024
	ds_read_b128 v[178:181], v152 offset:2048
	ds_read_b128 v[182:185], v152 offset:3072
	s_add_u32 s34, s30, 0xfffc0080
	s_addc_u32 s35, s31, -1
	s_cmp_eq_u32 s55, 12
	s_cselect_b32 s37, s23, s35
	s_cselect_b32 s36, s51, s34
	s_cselect_b32 s35, s21, s54
	s_cselect_b32 s34, s52, s53
	v_lshl_add_u64 v[174:175], s[30:31], 0, v[136:137]
	s_add_i32 m0, s29, 0xc000
	ds_read_b128 v[186:189], v153
	ds_read_b128 v[190:193], v153 offset:1024
	ds_read_b128 v[194:197], v153 offset:2048
	ds_read_b128 v[198:201], v153 offset:3072
	ds_read_b128 v[202:205], v153 offset:4096
	ds_read_b128 v[206:209], v153 offset:5120
	ds_read_b128 v[210:213], v153 offset:6144
	ds_read_b128 v[214:217], v153 offset:7168
	global_load_lds_dwordx4 v[174:175], off
	v_lshl_add_u64 v[174:175], s[30:31], 0, v[138:139]
	s_add_i32 m0, s29, 0xe000
	s_nop 0
	global_load_lds_dwordx4 v[174:175], off
	s_waitcnt vmcnt(8)
	s_waitcnt lgkmcnt(0)
	s_barrier
	s_setprio 1
	s_waitcnt lgkmcnt(0)
	v_mfma_f32_16x16x32_bf16 v[124:127], v[144:147], v[186:189], v[124:127]
	v_mfma_f32_16x16x32_bf16 v[116:119], v[158:161], v[186:189], v[116:119]
	v_mfma_f32_16x16x32_bf16 v[108:111], v[144:147], v[194:197], v[108:111]
	v_mfma_f32_16x16x32_bf16 v[100:103], v[158:161], v[194:197], v[100:103]
	v_mfma_f32_16x16x32_bf16 v[92:95], v[144:147], v[202:205], v[92:95]
	v_mfma_f32_16x16x32_bf16 v[84:87], v[158:161], v[202:205], v[84:87]
	v_mfma_f32_16x16x32_bf16 v[76:79], v[144:147], v[210:213], v[76:79]
	v_mfma_f32_16x16x32_bf16 v[68:71], v[158:161], v[210:213], v[68:71]
	v_mfma_f32_16x16x32_bf16 v[124:127], v[154:157], v[190:193], v[124:127]
	v_mfma_f32_16x16x32_bf16 v[116:119], v[162:165], v[190:193], v[116:119]
	v_mfma_f32_16x16x32_bf16 v[108:111], v[154:157], v[198:201], v[108:111]
	v_mfma_f32_16x16x32_bf16 v[100:103], v[162:165], v[198:201], v[100:103]
	v_mfma_f32_16x16x32_bf16 v[92:95], v[154:157], v[206:209], v[92:95]
	v_mfma_f32_16x16x32_bf16 v[84:87], v[162:165], v[206:209], v[84:87]
	v_mfma_f32_16x16x32_bf16 v[76:79], v[154:157], v[214:217], v[76:79]
	v_mfma_f32_16x16x32_bf16 v[68:71], v[162:165], v[214:217], v[68:71]
	s_setprio 0
	s_setprio 1
	v_mfma_f32_16x16x32_bf16 v[120:123], v[166:169], v[186:189], v[120:123]
	v_mfma_f32_16x16x32_bf16 v[112:115], v[178:181], v[186:189], v[112:115]
	v_mfma_f32_16x16x32_bf16 v[104:107], v[166:169], v[194:197], v[104:107]
	v_mfma_f32_16x16x32_bf16 v[96:99], v[178:181], v[194:197], v[96:99]
	v_mfma_f32_16x16x32_bf16 v[88:91], v[166:169], v[202:205], v[88:91]
	v_mfma_f32_16x16x32_bf16 v[80:83], v[178:181], v[202:205], v[80:83]
	v_mfma_f32_16x16x32_bf16 v[72:75], v[166:169], v[210:213], v[72:75]
	v_mfma_f32_16x16x32_bf16 v[64:67], v[178:181], v[210:213], v[64:67]
	v_mfma_f32_16x16x32_bf16 v[120:123], v[170:173], v[190:193], v[120:123]
	v_mfma_f32_16x16x32_bf16 v[112:115], v[182:185], v[190:193], v[112:115]
	v_mfma_f32_16x16x32_bf16 v[104:107], v[170:173], v[198:201], v[104:107]
	v_mfma_f32_16x16x32_bf16 v[96:99], v[182:185], v[198:201], v[96:99]
	v_mfma_f32_16x16x32_bf16 v[88:91], v[170:173], v[206:209], v[88:91]
	v_mfma_f32_16x16x32_bf16 v[80:83], v[182:185], v[206:209], v[80:83]
	v_mfma_f32_16x16x32_bf16 v[72:75], v[170:173], v[214:217], v[72:75]
	v_mfma_f32_16x16x32_bf16 v[64:67], v[182:185], v[214:217], v[64:67]
	s_setprio 0
	s_barrier
	s_add_i32 s56, s46, s39
	v_lshl_add_u64 v[174:175], s[34:35], 0, v[132:133]
	s_mov_b32 m0, s56
	ds_read_b128 v[186:189], v153 offset:16384
	ds_read_b128 v[190:193], v153 offset:17408
	ds_read_b128 v[194:197], v153 offset:18432
	ds_read_b128 v[198:201], v153 offset:19456
	ds_read_b128 v[202:205], v153 offset:20480
	ds_read_b128 v[206:209], v153 offset:21504
	ds_read_b128 v[210:213], v153 offset:22528
	ds_read_b128 v[214:217], v153 offset:23552
	global_load_lds_dwordx4 v[174:175], off
	s_add_i32 m0, s56, 0x2000
	s_add_u32 s56, s34, 0x40000
	v_lshl_add_u64 v[218:219], s[34:35], 0, v[128:129]
	s_addc_u32 s57, s35, 0
	s_add_i32 s58, s47, s39
	global_load_lds_dwordx4 v[218:219], off
	v_lshl_add_u64 v[220:221], s[56:57], 0, v[132:133]
	s_mov_b32 m0, s58
	v_lshl_add_u64 v[222:223], s[36:37], 0, v[130:131]
	global_load_lds_dwordx4 v[220:221], off
	v_lshl_add_u64 v[220:221], s[56:57], 0, v[128:129]
	s_add_i32 m0, s58, 0x2000
	s_nop 0
	global_load_lds_dwordx4 v[220:221], off
	v_lshl_add_u64 v[220:221], s[36:37], 0, v[134:135]
	s_mov_b32 m0, s29
	s_nop 0
	global_load_lds_dwordx4 v[220:221], off
	s_mov_b32 m0, s40
	s_nop 0
	global_load_lds_dwordx4 v[222:223], off
	s_waitcnt vmcnt(8)
	s_waitcnt lgkmcnt(0)
	s_barrier
	s_setprio 1
	s_waitcnt lgkmcnt(0)
	v_mfma_f32_16x16x32_bf16 v[60:63], v[144:147], v[186:189], v[60:63]
	v_mfma_f32_16x16x32_bf16 v[52:55], v[158:161], v[186:189], v[52:55]
	v_mfma_f32_16x16x32_bf16 v[44:47], v[144:147], v[194:197], v[44:47]
	v_mfma_f32_16x16x32_bf16 v[36:39], v[158:161], v[194:197], v[36:39]
	v_mfma_f32_16x16x32_bf16 v[28:31], v[144:147], v[202:205], v[28:31]
	v_mfma_f32_16x16x32_bf16 v[20:23], v[158:161], v[202:205], v[20:23]
	v_mfma_f32_16x16x32_bf16 v[12:15], v[144:147], v[210:213], v[12:15]
	v_mfma_f32_16x16x32_bf16 v[4:7], v[158:161], v[210:213], v[4:7]
	v_mfma_f32_16x16x32_bf16 v[60:63], v[154:157], v[190:193], v[60:63]
	v_mfma_f32_16x16x32_bf16 v[52:55], v[162:165], v[190:193], v[52:55]
	v_mfma_f32_16x16x32_bf16 v[44:47], v[154:157], v[198:201], v[44:47]
	v_mfma_f32_16x16x32_bf16 v[36:39], v[162:165], v[198:201], v[36:39]
	v_mfma_f32_16x16x32_bf16 v[28:31], v[154:157], v[206:209], v[28:31]
	v_mfma_f32_16x16x32_bf16 v[20:23], v[162:165], v[206:209], v[20:23]
	v_mfma_f32_16x16x32_bf16 v[12:15], v[154:157], v[214:217], v[12:15]
	v_mfma_f32_16x16x32_bf16 v[4:7], v[162:165], v[214:217], v[4:7]
	s_setprio 0
	s_setprio 1
	v_mfma_f32_16x16x32_bf16 v[56:59], v[166:169], v[186:189], v[56:59]
	v_mfma_f32_16x16x32_bf16 v[48:51], v[178:181], v[186:189], v[48:51]
	v_mfma_f32_16x16x32_bf16 v[40:43], v[166:169], v[194:197], v[40:43]
	v_mfma_f32_16x16x32_bf16 v[32:35], v[178:181], v[194:197], v[32:35]
	v_mfma_f32_16x16x32_bf16 v[24:27], v[166:169], v[202:205], v[24:27]
	v_mfma_f32_16x16x32_bf16 v[16:19], v[178:181], v[202:205], v[16:19]
	v_mfma_f32_16x16x32_bf16 v[8:11], v[166:169], v[210:213], v[8:11]
	v_mfma_f32_16x16x32_bf16 v[0:3], v[178:181], v[210:213], v[0:3]
	v_mfma_f32_16x16x32_bf16 v[56:59], v[170:173], v[190:193], v[56:59]
	v_mfma_f32_16x16x32_bf16 v[48:51], v[182:185], v[190:193], v[48:51]
	v_mfma_f32_16x16x32_bf16 v[40:43], v[170:173], v[198:201], v[40:43]
	v_mfma_f32_16x16x32_bf16 v[32:35], v[182:185], v[198:201], v[32:35]
	v_mfma_f32_16x16x32_bf16 v[24:27], v[170:173], v[206:209], v[24:27]
	v_mfma_f32_16x16x32_bf16 v[16:19], v[182:185], v[206:209], v[16:19]
	v_mfma_f32_16x16x32_bf16 v[8:11], v[170:173], v[214:217], v[8:11]
	v_mfma_f32_16x16x32_bf16 v[0:3], v[182:185], v[214:217], v[0:3]
	s_setprio 0
	s_barrier
	s_add_i32 s56, 0, 0x18000
	s_add_i32 s57, 0, 0x1c000
	v_add_u32_e32 v162, s56, v149
	v_add_u32_e32 v176, s57, v149
	ds_read_b128 v[144:147], v162
	ds_read_b128 v[154:157], v162 offset:1024
	ds_read_b128 v[158:161], v162 offset:2048
	ds_read_b128 v[162:165], v162 offset:3072
	ds_read_b128 v[166:169], v176
	ds_read_b128 v[170:173], v176 offset:1024
	ds_read_b128 v[178:181], v176 offset:2048
	ds_read_b128 v[182:185], v176 offset:3072
	s_add_u32 s36, s36, 0x40000
	s_addc_u32 s37, s37, 0
	s_mov_b32 m0, s41
	v_lshl_add_u64 v[224:225], s[36:37], 0, v[134:135]
	ds_read_b128 v[186:189], v153 offset:32768
	ds_read_b128 v[190:193], v153 offset:33792
	ds_read_b128 v[194:197], v153 offset:34816
	ds_read_b128 v[198:201], v153 offset:35840
	ds_read_b128 v[202:205], v153 offset:36864
	ds_read_b128 v[206:209], v153 offset:37888
	ds_read_b128 v[210:213], v153 offset:38912
	ds_read_b128 v[214:217], v153 offset:39936
	global_load_lds_dwordx4 v[224:225], off
	v_lshl_add_u64 v[224:225], s[36:37], 0, v[130:131]
	s_mov_b32 m0, s42
	s_nop 0
	global_load_lds_dwordx4 v[224:225], off
	s_waitcnt vmcnt(8)
	s_waitcnt lgkmcnt(0)
	s_barrier
	s_setprio 1
	s_waitcnt lgkmcnt(0)
	v_mfma_f32_16x16x32_bf16 v[124:127], v[144:147], v[186:189], v[124:127]
	v_mfma_f32_16x16x32_bf16 v[116:119], v[158:161], v[186:189], v[116:119]
	v_mfma_f32_16x16x32_bf16 v[108:111], v[144:147], v[194:197], v[108:111]
	v_mfma_f32_16x16x32_bf16 v[100:103], v[158:161], v[194:197], v[100:103]
	v_mfma_f32_16x16x32_bf16 v[92:95], v[144:147], v[202:205], v[92:95]
	v_mfma_f32_16x16x32_bf16 v[84:87], v[158:161], v[202:205], v[84:87]
	v_mfma_f32_16x16x32_bf16 v[76:79], v[144:147], v[210:213], v[76:79]
	v_mfma_f32_16x16x32_bf16 v[68:71], v[158:161], v[210:213], v[68:71]
	v_mfma_f32_16x16x32_bf16 v[124:127], v[154:157], v[190:193], v[124:127]
	v_mfma_f32_16x16x32_bf16 v[116:119], v[162:165], v[190:193], v[116:119]
	v_mfma_f32_16x16x32_bf16 v[108:111], v[154:157], v[198:201], v[108:111]
	v_mfma_f32_16x16x32_bf16 v[100:103], v[162:165], v[198:201], v[100:103]
	v_mfma_f32_16x16x32_bf16 v[92:95], v[154:157], v[206:209], v[92:95]
	v_mfma_f32_16x16x32_bf16 v[84:87], v[162:165], v[206:209], v[84:87]
	v_mfma_f32_16x16x32_bf16 v[76:79], v[154:157], v[214:217], v[76:79]
	v_mfma_f32_16x16x32_bf16 v[68:71], v[162:165], v[214:217], v[68:71]
	s_setprio 0
	s_setprio 1
	v_mfma_f32_16x16x32_bf16 v[120:123], v[166:169], v[186:189], v[120:123]
	v_mfma_f32_16x16x32_bf16 v[112:115], v[178:181], v[186:189], v[112:115]
	v_mfma_f32_16x16x32_bf16 v[104:107], v[166:169], v[194:197], v[104:107]
	v_mfma_f32_16x16x32_bf16 v[96:99], v[178:181], v[194:197], v[96:99]
	v_mfma_f32_16x16x32_bf16 v[88:91], v[166:169], v[202:205], v[88:91]
	v_mfma_f32_16x16x32_bf16 v[80:83], v[178:181], v[202:205], v[80:83]
	v_mfma_f32_16x16x32_bf16 v[72:75], v[166:169], v[210:213], v[72:75]
	v_mfma_f32_16x16x32_bf16 v[64:67], v[178:181], v[210:213], v[64:67]
	v_mfma_f32_16x16x32_bf16 v[120:123], v[170:173], v[190:193], v[120:123]
	v_mfma_f32_16x16x32_bf16 v[112:115], v[182:185], v[190:193], v[112:115]
	v_mfma_f32_16x16x32_bf16 v[104:107], v[170:173], v[198:201], v[104:107]
	v_mfma_f32_16x16x32_bf16 v[96:99], v[182:185], v[198:201], v[96:99]
	v_mfma_f32_16x16x32_bf16 v[88:91], v[170:173], v[206:209], v[88:91]
	v_mfma_f32_16x16x32_bf16 v[80:83], v[182:185], v[206:209], v[80:83]
	v_mfma_f32_16x16x32_bf16 v[72:75], v[170:173], v[214:217], v[72:75]
	v_mfma_f32_16x16x32_bf16 v[64:67], v[182:185], v[214:217], v[64:67]
	s_setprio 0
	s_barrier
	s_add_i32 s36, s56, s39
	v_lshl_add_u64 v[174:175], v[174:175], 0, s[16:17]
	s_mov_b32 m0, s36
	ds_read_b128 v[186:189], v153 offset:49152
	ds_read_b128 v[190:193], v153 offset:50176
	ds_read_b128 v[194:197], v153 offset:51200
	ds_read_b128 v[198:201], v153 offset:52224
	ds_read_b128 v[202:205], v153 offset:53248
	ds_read_b128 v[206:209], v153 offset:54272
	ds_read_b128 v[210:213], v153 offset:55296
	ds_read_b128 v[214:217], v153 offset:56320
	global_load_lds_dwordx4 v[174:175], off
	s_add_i32 m0, s36, 0x2000
	s_add_u32 s34, s34, 0x40080
	v_lshl_add_u64 v[174:175], v[218:219], 0, s[16:17]
	s_addc_u32 s35, s35, 0
	s_add_i32 s36, s57, s39
	global_load_lds_dwordx4 v[174:175], off
	v_lshl_add_u64 v[174:175], s[34:35], 0, v[132:133]
	s_mov_b32 m0, s36
	s_nop 0
	global_load_lds_dwordx4 v[174:175], off
	v_lshl_add_u64 v[174:175], s[34:35], 0, v[128:129]
	s_add_i32 m0, s36, 0x2000
	s_nop 0
	global_load_lds_dwordx4 v[174:175], off
	v_lshl_add_u64 v[174:175], v[220:221], 0, s[16:17]
	s_mov_b32 m0, s44
	s_nop 0
	global_load_lds_dwordx4 v[174:175], off
	v_lshl_add_u64 v[174:175], v[222:223], 0, s[16:17]
	s_mov_b32 m0, s45
	s_nop 0
	global_load_lds_dwordx4 v[174:175], off
	s_waitcnt vmcnt(8)
	s_waitcnt lgkmcnt(0)
	s_barrier
	s_setprio 1
	s_waitcnt lgkmcnt(0)
	v_mfma_f32_16x16x32_bf16 v[60:63], v[144:147], v[186:189], v[60:63]
	v_mfma_f32_16x16x32_bf16 v[52:55], v[158:161], v[186:189], v[52:55]
	v_mfma_f32_16x16x32_bf16 v[44:47], v[144:147], v[194:197], v[44:47]
	v_mfma_f32_16x16x32_bf16 v[36:39], v[158:161], v[194:197], v[36:39]
	v_mfma_f32_16x16x32_bf16 v[28:31], v[144:147], v[202:205], v[28:31]
	v_mfma_f32_16x16x32_bf16 v[20:23], v[158:161], v[202:205], v[20:23]
	v_mfma_f32_16x16x32_bf16 v[12:15], v[144:147], v[210:213], v[12:15]
	v_mfma_f32_16x16x32_bf16 v[4:7], v[158:161], v[210:213], v[4:7]
	v_mfma_f32_16x16x32_bf16 v[60:63], v[154:157], v[190:193], v[60:63]
	v_mfma_f32_16x16x32_bf16 v[52:55], v[162:165], v[190:193], v[52:55]
	v_mfma_f32_16x16x32_bf16 v[44:47], v[154:157], v[198:201], v[44:47]
	v_mfma_f32_16x16x32_bf16 v[36:39], v[162:165], v[198:201], v[36:39]
	v_mfma_f32_16x16x32_bf16 v[28:31], v[154:157], v[206:209], v[28:31]
	v_mfma_f32_16x16x32_bf16 v[20:23], v[162:165], v[206:209], v[20:23]
	v_mfma_f32_16x16x32_bf16 v[12:15], v[154:157], v[214:217], v[12:15]
	v_mfma_f32_16x16x32_bf16 v[4:7], v[162:165], v[214:217], v[4:7]
	s_setprio 0
	s_setprio 1
	v_mfma_f32_16x16x32_bf16 v[56:59], v[166:169], v[186:189], v[56:59]
	v_mfma_f32_16x16x32_bf16 v[48:51], v[178:181], v[186:189], v[48:51]
	v_mfma_f32_16x16x32_bf16 v[40:43], v[166:169], v[194:197], v[40:43]
	v_mfma_f32_16x16x32_bf16 v[32:35], v[178:181], v[194:197], v[32:35]
	v_mfma_f32_16x16x32_bf16 v[24:27], v[166:169], v[202:205], v[24:27]
	v_mfma_f32_16x16x32_bf16 v[16:19], v[178:181], v[202:205], v[16:19]
	v_mfma_f32_16x16x32_bf16 v[8:11], v[166:169], v[210:213], v[8:11]
	v_mfma_f32_16x16x32_bf16 v[0:3], v[178:181], v[210:213], v[0:3]
	v_mfma_f32_16x16x32_bf16 v[56:59], v[170:173], v[190:193], v[56:59]
	v_mfma_f32_16x16x32_bf16 v[48:51], v[182:185], v[190:193], v[48:51]
	v_mfma_f32_16x16x32_bf16 v[40:43], v[170:173], v[198:201], v[40:43]
	v_mfma_f32_16x16x32_bf16 v[32:35], v[182:185], v[198:201], v[32:35]
	v_mfma_f32_16x16x32_bf16 v[24:27], v[170:173], v[206:209], v[24:27]
	v_mfma_f32_16x16x32_bf16 v[16:19], v[182:185], v[206:209], v[16:19]
	v_mfma_f32_16x16x32_bf16 v[8:11], v[170:173], v[214:217], v[8:11]
	v_mfma_f32_16x16x32_bf16 v[0:3], v[182:185], v[214:217], v[0:3]
	s_setprio 0
	s_barrier
	s_add_i32 s55, s55, 2
	s_add_u32 s30, s30, 0x100
	s_addc_u32 s31, s31, 0
	s_add_u32 s53, s53, 0x100
	s_addc_u32 s54, s54, 0
	s_cmp_gt_u32 s55, 13
	s_cbranch_scc0 .LBB0_128
	s_and_b64 vcc, exec, s[18:19]
	s_cbranch_vccz .LBB0_131
	s_and_b64 vcc, exec, s[6:7]
	s_cbranch_vccnz .LBB0_131
	s_barrier
.LBB0_131:
	v_mul_f32_e32 v155, 0xbfb8aa3b, v124
	v_exp_f32_e32 v155, v155
	v_mul_f32_e32 v158, 0xbfb8aa3b, v125
	v_exp_f32_e32 v159, v158
	v_lshl_add_u32 v154, s28, 8, v148
	v_add_f32_e32 v155, 1.0, v155
	v_rcp_f32_e32 v158, v155
	v_add_f32_e32 v155, 1.0, v159
	v_mul_f32_e32 v159, 0xbfb8aa3b, v126
	v_exp_f32_e32 v160, v159
	v_mul_f32_e32 v159, 0xbfb8aa3b, v127
	v_exp_f32_e32 v161, v159
	v_rcp_f32_e32 v159, v155
	v_add_f32_e32 v155, 1.0, v160
	v_rcp_f32_e32 v160, v155
	v_add_f32_e32 v155, 1.0, v161
	v_rcp_f32_e32 v161, v155
	v_pk_mul_f32 v[124:125], v[124:125], v[158:159]
	v_lshl_or_b32 v144, s49, 7, v150
	v_pk_mul_f32 v[120:121], v[124:125], v[120:121]
	v_pk_mul_f32 v[124:125], v[126:127], v[160:161]
	v_cvt_pk_bf16_f32 v120, v120, v121
	v_mul_f32_e32 v121, 0xbfb8aa3b, v116
	v_pk_mul_f32 v[122:123], v[124:125], v[122:123]
	v_exp_f32_e32 v124, v121
	v_mul_f32_e32 v121, 0xbfb8aa3b, v117
	v_exp_f32_e32 v125, v121
	v_cvt_pk_bf16_f32 v121, v122, v123
	v_add_f32_e32 v122, 1.0, v124
	v_mul_f32_e32 v124, 0xbfb8aa3b, v118
	v_add_f32_e32 v123, 1.0, v125
	v_mul_f32_e32 v125, 0xbfb8aa3b, v119
	v_exp_f32_e32 v124, v124
	v_exp_f32_e32 v125, v125
	v_rcp_f32_e32 v122, v122
	v_rcp_f32_e32 v123, v123
	v_add_f32_e32 v124, 1.0, v124
	v_add_f32_e32 v125, 1.0, v125
	v_rcp_f32_e32 v124, v124
	v_rcp_f32_e32 v125, v125
	v_pk_mul_f32 v[116:117], v[116:117], v[122:123]
	v_ashrrev_i32_e32 v145, 31, v144
	v_pk_mul_f32 v[112:113], v[116:117], v[112:113]
	v_mul_f32_e32 v116, 0xbfb8aa3b, v110
	v_cvt_pk_bf16_f32 v122, v112, v113
	v_pk_mul_f32 v[112:113], v[118:119], v[124:125]
	v_mul_f32_e32 v117, 0xbfb8aa3b, v111
	v_pk_mul_f32 v[112:113], v[112:113], v[114:115]
	v_mul_f32_e32 v114, 0xbfb8aa3b, v108
	v_mul_f32_e32 v115, 0xbfb8aa3b, v109
	v_exp_f32_e32 v114, v114
	v_exp_f32_e32 v115, v115
	v_exp_f32_e32 v116, v116
	v_exp_f32_e32 v117, v117
	v_add_f32_e32 v114, 1.0, v114
	v_add_f32_e32 v115, 1.0, v115
	v_rcp_f32_e32 v114, v114
	v_rcp_f32_e32 v115, v115
	v_add_f32_e32 v116, 1.0, v116
	v_add_f32_e32 v117, 1.0, v117
	v_rcp_f32_e32 v116, v116
	v_rcp_f32_e32 v117, v117
	v_pk_mul_f32 v[108:109], v[108:109], v[114:115]
	v_mov_b64_e32 v[146:147], s[14:15]
	v_pk_mul_f32 v[104:105], v[108:109], v[104:105]
	v_pk_mul_f32 v[108:109], v[110:111], v[116:117]
	v_cvt_pk_bf16_f32 v104, v104, v105
	v_mul_f32_e32 v105, 0xbfb8aa3b, v100
	v_pk_mul_f32 v[106:107], v[108:109], v[106:107]
	v_exp_f32_e32 v108, v105
	v_mul_f32_e32 v105, 0xbfb8aa3b, v101
	v_exp_f32_e32 v109, v105
	v_cvt_pk_bf16_f32 v105, v106, v107
	v_add_f32_e32 v106, 1.0, v108
	v_mul_f32_e32 v108, 0xbfb8aa3b, v102
	v_add_f32_e32 v107, 1.0, v109
	v_mul_f32_e32 v109, 0xbfb8aa3b, v103
	v_exp_f32_e32 v108, v108
	v_exp_f32_e32 v109, v109
	v_rcp_f32_e32 v106, v106
	v_rcp_f32_e32 v107, v107
	v_add_f32_e32 v108, 1.0, v108
	v_add_f32_e32 v109, 1.0, v109
	v_rcp_f32_e32 v108, v108
	v_rcp_f32_e32 v109, v109
	v_pk_mul_f32 v[100:101], v[100:101], v[106:107]
	v_cvt_pk_bf16_f32 v123, v112, v113
	v_pk_mul_f32 v[96:97], v[100:101], v[96:97]
	v_mul_f32_e32 v100, 0xbfb8aa3b, v94
	v_cvt_pk_bf16_f32 v106, v96, v97
	v_pk_mul_f32 v[96:97], v[102:103], v[108:109]
	v_mul_f32_e32 v101, 0xbfb8aa3b, v95
	v_pk_mul_f32 v[96:97], v[96:97], v[98:99]
	v_mul_f32_e32 v98, 0xbfb8aa3b, v92
	v_mul_f32_e32 v99, 0xbfb8aa3b, v93
	v_exp_f32_e32 v98, v98
	v_exp_f32_e32 v99, v99
	v_exp_f32_e32 v100, v100
	v_exp_f32_e32 v101, v101
	v_add_f32_e32 v98, 1.0, v98
	v_add_f32_e32 v99, 1.0, v99
	v_rcp_f32_e32 v98, v98
	v_rcp_f32_e32 v99, v99
	v_add_f32_e32 v100, 1.0, v100
	v_add_f32_e32 v101, 1.0, v101
	v_rcp_f32_e32 v100, v100
	v_rcp_f32_e32 v101, v101
	v_pk_mul_f32 v[92:93], v[92:93], v[98:99]
	v_or_b32_e32 v112, 16, v154
	v_pk_mul_f32 v[88:89], v[92:93], v[88:89]
	v_pk_mul_f32 v[92:93], v[94:95], v[100:101]
	v_cvt_pk_bf16_f32 v88, v88, v89
	v_mul_f32_e32 v89, 0xbfb8aa3b, v84
	v_pk_mul_f32 v[90:91], v[92:93], v[90:91]
	v_exp_f32_e32 v92, v89
	v_mul_f32_e32 v89, 0xbfb8aa3b, v85
	v_exp_f32_e32 v93, v89
	v_cvt_pk_bf16_f32 v89, v90, v91
	v_add_f32_e32 v90, 1.0, v92
	v_mul_f32_e32 v92, 0xbfb8aa3b, v86
	v_add_f32_e32 v91, 1.0, v93
	v_mul_f32_e32 v93, 0xbfb8aa3b, v87
	v_exp_f32_e32 v92, v92
	v_exp_f32_e32 v93, v93
	v_rcp_f32_e32 v90, v90
	v_rcp_f32_e32 v91, v91
	v_add_f32_e32 v92, 1.0, v92
	v_add_f32_e32 v93, 1.0, v93
	v_rcp_f32_e32 v92, v92
	v_rcp_f32_e32 v93, v93
	v_pk_mul_f32 v[84:85], v[84:85], v[90:91]
	v_cvt_pk_bf16_f32 v107, v96, v97
	v_pk_mul_f32 v[80:81], v[84:85], v[80:81]
	v_mul_f32_e32 v84, 0xbfb8aa3b, v78
	v_cvt_pk_bf16_f32 v90, v80, v81
	v_pk_mul_f32 v[80:81], v[86:87], v[92:93]
	v_mul_f32_e32 v85, 0xbfb8aa3b, v79
	v_pk_mul_f32 v[80:81], v[80:81], v[82:83]
	v_mul_f32_e32 v82, 0xbfb8aa3b, v76
	v_mul_f32_e32 v83, 0xbfb8aa3b, v77
	v_exp_f32_e32 v82, v82
	v_exp_f32_e32 v83, v83
	v_exp_f32_e32 v84, v84
	v_exp_f32_e32 v85, v85
	v_add_f32_e32 v82, 1.0, v82
	v_add_f32_e32 v83, 1.0, v83
	v_rcp_f32_e32 v82, v82
	v_rcp_f32_e32 v83, v83
	v_add_f32_e32 v84, 1.0, v84
	v_add_f32_e32 v85, 1.0, v85
	v_rcp_f32_e32 v84, v84
	v_rcp_f32_e32 v85, v85
	v_pk_mul_f32 v[76:77], v[76:77], v[82:83]
	v_or_b32_e32 v96, 32, v154
	v_pk_mul_f32 v[72:73], v[76:77], v[72:73]
	v_pk_mul_f32 v[76:77], v[78:79], v[84:85]
	v_cvt_pk_bf16_f32 v72, v72, v73
	v_mul_f32_e32 v73, 0xbfb8aa3b, v68
	v_pk_mul_f32 v[74:75], v[76:77], v[74:75]
	v_exp_f32_e32 v76, v73
	v_mul_f32_e32 v73, 0xbfb8aa3b, v69
	v_exp_f32_e32 v77, v73
	v_cvt_pk_bf16_f32 v73, v74, v75
	v_add_f32_e32 v74, 1.0, v76
	v_mul_f32_e32 v76, 0xbfb8aa3b, v70
	v_add_f32_e32 v75, 1.0, v77
	v_mul_f32_e32 v77, 0xbfb8aa3b, v71
	v_exp_f32_e32 v76, v76
	v_exp_f32_e32 v77, v77
	v_rcp_f32_e32 v74, v74
	v_rcp_f32_e32 v75, v75
	v_add_f32_e32 v76, 1.0, v76
	v_add_f32_e32 v77, 1.0, v77
	v_rcp_f32_e32 v76, v76
	v_rcp_f32_e32 v77, v77
	v_pk_mul_f32 v[68:69], v[68:69], v[74:75]
	v_cvt_pk_bf16_f32 v91, v80, v81
	v_pk_mul_f32 v[64:65], v[68:69], v[64:65]
	v_mul_f32_e32 v68, 0xbfb8aa3b, v62
	v_cvt_pk_bf16_f32 v74, v64, v65
	v_pk_mul_f32 v[64:65], v[70:71], v[76:77]
	v_mul_f32_e32 v69, 0xbfb8aa3b, v63
	v_pk_mul_f32 v[64:65], v[64:65], v[66:67]
	v_mul_f32_e32 v66, 0xbfb8aa3b, v60
	v_mul_f32_e32 v67, 0xbfb8aa3b, v61
	v_exp_f32_e32 v66, v66
	v_exp_f32_e32 v67, v67
	v_exp_f32_e32 v68, v68
	v_exp_f32_e32 v69, v69
	v_add_f32_e32 v66, 1.0, v66
	v_add_f32_e32 v67, 1.0, v67
	v_rcp_f32_e32 v66, v66
	v_rcp_f32_e32 v67, v67
	v_add_f32_e32 v68, 1.0, v68
	v_add_f32_e32 v69, 1.0, v69
	v_rcp_f32_e32 v68, v68
	v_rcp_f32_e32 v69, v69
	v_pk_mul_f32 v[60:61], v[60:61], v[66:67]
	v_or_b32_e32 v80, 48, v154
	v_pk_mul_f32 v[56:57], v[60:61], v[56:57]
	v_pk_mul_f32 v[60:61], v[62:63], v[68:69]
	v_cvt_pk_bf16_f32 v56, v56, v57
	v_mul_f32_e32 v57, 0xbfb8aa3b, v52
	v_pk_mul_f32 v[58:59], v[60:61], v[58:59]
	v_exp_f32_e32 v60, v57
	v_mul_f32_e32 v57, 0xbfb8aa3b, v53
	v_exp_f32_e32 v61, v57
	v_cvt_pk_bf16_f32 v57, v58, v59
	v_add_f32_e32 v58, 1.0, v60
	v_mul_f32_e32 v60, 0xbfb8aa3b, v54
	v_add_f32_e32 v59, 1.0, v61
	v_mul_f32_e32 v61, 0xbfb8aa3b, v55
	v_exp_f32_e32 v60, v60
	v_exp_f32_e32 v61, v61
	v_rcp_f32_e32 v58, v58
	v_rcp_f32_e32 v59, v59
	v_add_f32_e32 v60, 1.0, v60
	v_add_f32_e32 v61, 1.0, v61
	v_rcp_f32_e32 v60, v60
	v_rcp_f32_e32 v61, v61
	v_pk_mul_f32 v[52:53], v[52:53], v[58:59]
	v_cvt_pk_bf16_f32 v75, v64, v65
	v_pk_mul_f32 v[48:49], v[52:53], v[48:49]
	v_mul_f32_e32 v52, 0xbfb8aa3b, v46
	v_cvt_pk_bf16_f32 v58, v48, v49
	v_pk_mul_f32 v[48:49], v[54:55], v[60:61]
	v_mul_f32_e32 v53, 0xbfb8aa3b, v47
	v_pk_mul_f32 v[48:49], v[48:49], v[50:51]
	v_mul_f32_e32 v50, 0xbfb8aa3b, v44
	v_mul_f32_e32 v51, 0xbfb8aa3b, v45
	v_exp_f32_e32 v50, v50
	v_exp_f32_e32 v51, v51
	v_exp_f32_e32 v52, v52
	v_exp_f32_e32 v53, v53
	v_add_f32_e32 v50, 1.0, v50
	v_add_f32_e32 v51, 1.0, v51
	v_rcp_f32_e32 v50, v50
	v_rcp_f32_e32 v51, v51
	v_add_f32_e32 v52, 1.0, v52
	v_add_f32_e32 v53, 1.0, v53
	v_rcp_f32_e32 v52, v52
	v_rcp_f32_e32 v53, v53
	v_pk_mul_f32 v[44:45], v[44:45], v[50:51]
	v_add_u32_e32 v64, 0x80, v154
	v_pk_mul_f32 v[40:41], v[44:45], v[40:41]
	v_pk_mul_f32 v[44:45], v[46:47], v[52:53]
	v_cvt_pk_bf16_f32 v40, v40, v41
	v_mul_f32_e32 v41, 0xbfb8aa3b, v36
	v_pk_mul_f32 v[42:43], v[44:45], v[42:43]
	v_exp_f32_e32 v44, v41
	v_mul_f32_e32 v41, 0xbfb8aa3b, v37
	v_exp_f32_e32 v45, v41
	v_cvt_pk_bf16_f32 v41, v42, v43
	v_add_f32_e32 v42, 1.0, v44
	v_mul_f32_e32 v44, 0xbfb8aa3b, v38
	v_add_f32_e32 v43, 1.0, v45
	v_mul_f32_e32 v45, 0xbfb8aa3b, v39
	v_exp_f32_e32 v44, v44
	v_exp_f32_e32 v45, v45
	v_rcp_f32_e32 v42, v42
	v_rcp_f32_e32 v43, v43
	v_add_f32_e32 v44, 1.0, v44
	v_add_f32_e32 v45, 1.0, v45
	v_rcp_f32_e32 v44, v44
	v_rcp_f32_e32 v45, v45
	v_pk_mul_f32 v[36:37], v[36:37], v[42:43]
	v_cvt_pk_bf16_f32 v59, v48, v49
	v_pk_mul_f32 v[32:33], v[36:37], v[32:33]
	v_mul_f32_e32 v36, 0xbfb8aa3b, v30
	v_cvt_pk_bf16_f32 v42, v32, v33
	v_pk_mul_f32 v[32:33], v[38:39], v[44:45]
	v_mul_f32_e32 v37, 0xbfb8aa3b, v31
	v_pk_mul_f32 v[32:33], v[32:33], v[34:35]
	v_mul_f32_e32 v34, 0xbfb8aa3b, v28
	v_mul_f32_e32 v35, 0xbfb8aa3b, v29
	v_exp_f32_e32 v34, v34
	v_exp_f32_e32 v35, v35
	v_exp_f32_e32 v36, v36
	v_exp_f32_e32 v37, v37
	v_add_f32_e32 v34, 1.0, v34
	v_add_f32_e32 v35, 1.0, v35
	v_rcp_f32_e32 v34, v34
	v_rcp_f32_e32 v35, v35
	v_add_f32_e32 v36, 1.0, v36
	v_add_f32_e32 v37, 1.0, v37
	v_rcp_f32_e32 v36, v36
	v_rcp_f32_e32 v37, v37
	v_pk_mul_f32 v[28:29], v[28:29], v[34:35]
	v_add_u32_e32 v48, 0x90, v154
	v_pk_mul_f32 v[24:25], v[28:29], v[24:25]
	v_pk_mul_f32 v[28:29], v[30:31], v[36:37]
	v_cvt_pk_bf16_f32 v24, v24, v25
	v_mul_f32_e32 v25, 0xbfb8aa3b, v20
	v_pk_mul_f32 v[26:27], v[28:29], v[26:27]
	v_exp_f32_e32 v28, v25
	v_mul_f32_e32 v25, 0xbfb8aa3b, v21
	v_exp_f32_e32 v29, v25
	v_cvt_pk_bf16_f32 v25, v26, v27
	v_add_f32_e32 v26, 1.0, v28
	v_mul_f32_e32 v28, 0xbfb8aa3b, v22
	v_add_f32_e32 v27, 1.0, v29
	v_mul_f32_e32 v29, 0xbfb8aa3b, v23
	v_exp_f32_e32 v28, v28
	v_exp_f32_e32 v29, v29
	v_rcp_f32_e32 v26, v26
	v_rcp_f32_e32 v27, v27
	v_add_f32_e32 v28, 1.0, v28
	v_add_f32_e32 v29, 1.0, v29
	v_rcp_f32_e32 v28, v28
	v_rcp_f32_e32 v29, v29
	v_pk_mul_f32 v[20:21], v[20:21], v[26:27]
	v_cvt_pk_bf16_f32 v43, v32, v33
	v_pk_mul_f32 v[16:17], v[20:21], v[16:17]
	v_mul_f32_e32 v20, 0xbfb8aa3b, v14
	v_cvt_pk_bf16_f32 v26, v16, v17
	v_pk_mul_f32 v[16:17], v[22:23], v[28:29]
	v_mul_f32_e32 v21, 0xbfb8aa3b, v15
	v_pk_mul_f32 v[16:17], v[16:17], v[18:19]
	v_mul_f32_e32 v18, 0xbfb8aa3b, v12
	v_mul_f32_e32 v19, 0xbfb8aa3b, v13
	v_exp_f32_e32 v18, v18
	v_exp_f32_e32 v19, v19
	v_exp_f32_e32 v20, v20
	v_exp_f32_e32 v21, v21
	v_add_f32_e32 v18, 1.0, v18
	v_add_f32_e32 v19, 1.0, v19
	v_rcp_f32_e32 v18, v18
	v_rcp_f32_e32 v19, v19
	v_add_f32_e32 v20, 1.0, v20
	v_add_f32_e32 v21, 1.0, v21
	v_rcp_f32_e32 v20, v20
	v_rcp_f32_e32 v21, v21
	v_pk_mul_f32 v[12:13], v[12:13], v[18:19]
	v_add_u32_e32 v32, 0xa0, v154
	v_pk_mul_f32 v[8:9], v[12:13], v[8:9]
	v_pk_mul_f32 v[12:13], v[14:15], v[20:21]
	v_cvt_pk_bf16_f32 v8, v8, v9
	v_mul_f32_e32 v9, 0xbfb8aa3b, v4
	v_pk_mul_f32 v[10:11], v[12:13], v[10:11]
	v_exp_f32_e32 v12, v9
	v_mul_f32_e32 v9, 0xbfb8aa3b, v5
	v_exp_f32_e32 v13, v9
	v_cvt_pk_bf16_f32 v9, v10, v11
	v_add_f32_e32 v10, 1.0, v12
	v_mul_f32_e32 v12, 0xbfb8aa3b, v6
	v_add_f32_e32 v11, 1.0, v13
	v_mul_f32_e32 v13, 0xbfb8aa3b, v7
	v_exp_f32_e32 v12, v12
	v_exp_f32_e32 v13, v13
	v_rcp_f32_e32 v10, v10
	v_rcp_f32_e32 v11, v11
	v_add_f32_e32 v12, 1.0, v12
	v_add_f32_e32 v13, 1.0, v13
	v_rcp_f32_e32 v12, v12
	v_rcp_f32_e32 v13, v13
	v_pk_mul_f32 v[4:5], v[4:5], v[10:11]
	v_cvt_pk_bf16_f32 v27, v16, v17
	v_pk_mul_f32 v[0:1], v[4:5], v[0:1]
	v_add_u32_e32 v16, 0xb0, v154
	v_cvt_pk_bf16_f32 v10, v0, v1
	v_pk_mul_f32 v[0:1], v[6:7], v[12:13]
	v_mad_i64_i32 v[156:157], s[30:31], v154, s48, v[146:147]
	v_lshlrev_b64 v[144:145], 1, v[144:145]
	v_mad_i64_i32 v[112:113], s[30:31], v112, s48, v[146:147]
	v_mad_i64_i32 v[96:97], s[30:31], v96, s48, v[146:147]
	v_mad_i64_i32 v[80:81], s[30:31], v80, s48, v[146:147]
	v_mad_i64_i32 v[64:65], s[30:31], v64, s48, v[146:147]
	v_mad_i64_i32 v[48:49], s[30:31], v48, s48, v[146:147]
	v_mad_i64_i32 v[32:33], s[30:31], v32, s48, v[146:147]
	v_mad_i64_i32 v[16:17], s[30:31], v16, s48, v[146:147]
	v_pk_mul_f32 v[0:1], v[0:1], v[2:3]
	v_lshl_add_u64 v[156:157], v[156:157], 0, v[144:145]
	v_lshl_add_u64 v[112:113], v[112:113], 0, v[144:145]
	v_lshl_add_u64 v[96:97], v[96:97], 0, v[144:145]
	v_lshl_add_u64 v[80:81], v[80:81], 0, v[144:145]
	v_lshl_add_u64 v[64:65], v[64:65], 0, v[144:145]
	v_lshl_add_u64 v[48:49], v[48:49], 0, v[144:145]
	v_lshl_add_u64 v[32:33], v[32:33], 0, v[144:145]
	v_lshl_add_u64 v[16:17], v[16:17], 0, v[144:145]
	v_cvt_pk_bf16_f32 v11, v0, v1
	s_andn2_b64 vcc, exec, s[6:7]
	s_mov_b64 s[6:7], -1
	global_store_dwordx4 v[156:157], v[120:123], off
	global_store_dwordx4 v[112:113], v[104:107], off
	global_store_dwordx4 v[96:97], v[88:91], off
	global_store_dwordx4 v[80:81], v[72:75], off
	global_store_dwordx4 v[64:65], v[56:59], off
	global_store_dwordx4 v[48:49], v[40:43], off
	global_store_dwordx4 v[32:33], v[24:27], off
	global_store_dwordx4 v[16:17], v[8:11], off
	s_cbranch_vccnz .LBB0_120
	s_andn2_b64 vcc, exec, s[4:5]
	s_cbranch_vccnz .LBB0_119
	s_branch .LBB0_119

.LBB0_1152:
	ds_read_b128 v[144:147], v151
	ds_read_b128 v[154:157], v151 offset:1024
	ds_read_b128 v[158:161], v151 offset:2048
	ds_read_b128 v[162:165], v151 offset:3072
	ds_read_b128 v[166:169], v152
	ds_read_b128 v[170:173], v152 offset:1024
	ds_read_b128 v[178:181], v152 offset:2048
	ds_read_b128 v[182:185], v152 offset:3072
	s_add_u32 s26, s24, 0xfffc0080
	s_addc_u32 s27, s25, -1
	s_cmp_eq_u32 s48, 12
	s_cselect_b32 s29, s17, s27
	s_cselect_b32 s28, s44, s26
	s_cselect_b32 s27, s15, s47
	s_cselect_b32 s26, s45, s46
	v_lshl_add_u64 v[174:175], s[24:25], 0, v[136:137]
	s_add_i32 m0, s23, 0xc000
	ds_read_b128 v[186:189], v153
	ds_read_b128 v[190:193], v153 offset:1024
	ds_read_b128 v[194:197], v153 offset:2048
	ds_read_b128 v[198:201], v153 offset:3072
	ds_read_b128 v[202:205], v153 offset:4096
	ds_read_b128 v[206:209], v153 offset:5120
	ds_read_b128 v[210:213], v153 offset:6144
	ds_read_b128 v[214:217], v153 offset:7168
	global_load_lds_dwordx4 v[174:175], off
	v_lshl_add_u64 v[174:175], s[24:25], 0, v[138:139]
	s_add_i32 m0, s23, 0xe000
	s_nop 0
	global_load_lds_dwordx4 v[174:175], off
	s_waitcnt vmcnt(8)
	s_waitcnt lgkmcnt(0)
	s_barrier
	s_setprio 1
	s_waitcnt lgkmcnt(0)
	v_mfma_f32_16x16x32_bf16 v[124:127], v[144:147], v[186:189], v[124:127]
	v_mfma_f32_16x16x32_bf16 v[116:119], v[158:161], v[186:189], v[116:119]
	v_mfma_f32_16x16x32_bf16 v[108:111], v[144:147], v[194:197], v[108:111]
	v_mfma_f32_16x16x32_bf16 v[100:103], v[158:161], v[194:197], v[100:103]
	v_mfma_f32_16x16x32_bf16 v[92:95], v[144:147], v[202:205], v[92:95]
	v_mfma_f32_16x16x32_bf16 v[84:87], v[158:161], v[202:205], v[84:87]
	v_mfma_f32_16x16x32_bf16 v[76:79], v[144:147], v[210:213], v[76:79]
	v_mfma_f32_16x16x32_bf16 v[68:71], v[158:161], v[210:213], v[68:71]
	v_mfma_f32_16x16x32_bf16 v[124:127], v[154:157], v[190:193], v[124:127]
	v_mfma_f32_16x16x32_bf16 v[116:119], v[162:165], v[190:193], v[116:119]
	v_mfma_f32_16x16x32_bf16 v[108:111], v[154:157], v[198:201], v[108:111]
	v_mfma_f32_16x16x32_bf16 v[100:103], v[162:165], v[198:201], v[100:103]
	v_mfma_f32_16x16x32_bf16 v[92:95], v[154:157], v[206:209], v[92:95]
	v_mfma_f32_16x16x32_bf16 v[84:87], v[162:165], v[206:209], v[84:87]
	v_mfma_f32_16x16x32_bf16 v[76:79], v[154:157], v[214:217], v[76:79]
	v_mfma_f32_16x16x32_bf16 v[68:71], v[162:165], v[214:217], v[68:71]
	s_setprio 0
	s_setprio 1
	v_mfma_f32_16x16x32_bf16 v[120:123], v[166:169], v[186:189], v[120:123]
	v_mfma_f32_16x16x32_bf16 v[112:115], v[178:181], v[186:189], v[112:115]
	v_mfma_f32_16x16x32_bf16 v[104:107], v[166:169], v[194:197], v[104:107]
	v_mfma_f32_16x16x32_bf16 v[96:99], v[178:181], v[194:197], v[96:99]
	v_mfma_f32_16x16x32_bf16 v[88:91], v[166:169], v[202:205], v[88:91]
	v_mfma_f32_16x16x32_bf16 v[80:83], v[178:181], v[202:205], v[80:83]
	v_mfma_f32_16x16x32_bf16 v[72:75], v[166:169], v[210:213], v[72:75]
	v_mfma_f32_16x16x32_bf16 v[64:67], v[178:181], v[210:213], v[64:67]
	v_mfma_f32_16x16x32_bf16 v[120:123], v[170:173], v[190:193], v[120:123]
	v_mfma_f32_16x16x32_bf16 v[112:115], v[182:185], v[190:193], v[112:115]
	v_mfma_f32_16x16x32_bf16 v[104:107], v[170:173], v[198:201], v[104:107]
	v_mfma_f32_16x16x32_bf16 v[96:99], v[182:185], v[198:201], v[96:99]
	v_mfma_f32_16x16x32_bf16 v[88:91], v[170:173], v[206:209], v[88:91]
	v_mfma_f32_16x16x32_bf16 v[80:83], v[182:185], v[206:209], v[80:83]
	v_mfma_f32_16x16x32_bf16 v[72:75], v[170:173], v[214:217], v[72:75]
	v_mfma_f32_16x16x32_bf16 v[64:67], v[182:185], v[214:217], v[64:67]
	s_setprio 0
	s_barrier
	s_add_i32 s49, s40, s33
	v_lshl_add_u64 v[174:175], s[26:27], 0, v[132:133]
	s_mov_b32 m0, s49
	ds_read_b128 v[186:189], v153 offset:16384
	ds_read_b128 v[190:193], v153 offset:17408
	ds_read_b128 v[194:197], v153 offset:18432
	ds_read_b128 v[198:201], v153 offset:19456
	ds_read_b128 v[202:205], v153 offset:20480
	ds_read_b128 v[206:209], v153 offset:21504
	ds_read_b128 v[210:213], v153 offset:22528
	ds_read_b128 v[214:217], v153 offset:23552
	global_load_lds_dwordx4 v[174:175], off
	s_add_i32 m0, s49, 0x2000
	s_add_u32 s50, s26, 0x40000
	v_lshl_add_u64 v[218:219], s[26:27], 0, v[128:129]
	s_addc_u32 s51, s27, 0
	s_add_i32 s49, s41, s33
	global_load_lds_dwordx4 v[218:219], off
	v_lshl_add_u64 v[220:221], s[50:51], 0, v[132:133]
	s_mov_b32 m0, s49
	v_lshl_add_u64 v[222:223], s[28:29], 0, v[130:131]
	global_load_lds_dwordx4 v[220:221], off
	v_lshl_add_u64 v[220:221], s[50:51], 0, v[128:129]
	s_add_i32 m0, s49, 0x2000
	s_nop 0
	global_load_lds_dwordx4 v[220:221], off
	v_lshl_add_u64 v[220:221], s[28:29], 0, v[134:135]
	s_mov_b32 m0, s23
	s_nop 0
	global_load_lds_dwordx4 v[220:221], off
	s_mov_b32 m0, s34
	s_nop 0
	global_load_lds_dwordx4 v[222:223], off
	s_waitcnt vmcnt(8)
	s_waitcnt lgkmcnt(0)
	s_barrier
	s_setprio 1
	s_waitcnt lgkmcnt(0)
	v_mfma_f32_16x16x32_bf16 v[60:63], v[144:147], v[186:189], v[60:63]
	v_mfma_f32_16x16x32_bf16 v[52:55], v[158:161], v[186:189], v[52:55]
	v_mfma_f32_16x16x32_bf16 v[44:47], v[144:147], v[194:197], v[44:47]
	v_mfma_f32_16x16x32_bf16 v[36:39], v[158:161], v[194:197], v[36:39]
	v_mfma_f32_16x16x32_bf16 v[28:31], v[144:147], v[202:205], v[28:31]
	v_mfma_f32_16x16x32_bf16 v[20:23], v[158:161], v[202:205], v[20:23]
	v_mfma_f32_16x16x32_bf16 v[12:15], v[144:147], v[210:213], v[12:15]
	v_mfma_f32_16x16x32_bf16 v[4:7], v[158:161], v[210:213], v[4:7]
	v_mfma_f32_16x16x32_bf16 v[60:63], v[154:157], v[190:193], v[60:63]
	v_mfma_f32_16x16x32_bf16 v[52:55], v[162:165], v[190:193], v[52:55]
	v_mfma_f32_16x16x32_bf16 v[44:47], v[154:157], v[198:201], v[44:47]
	v_mfma_f32_16x16x32_bf16 v[36:39], v[162:165], v[198:201], v[36:39]
	v_mfma_f32_16x16x32_bf16 v[28:31], v[154:157], v[206:209], v[28:31]
	v_mfma_f32_16x16x32_bf16 v[20:23], v[162:165], v[206:209], v[20:23]
	v_mfma_f32_16x16x32_bf16 v[12:15], v[154:157], v[214:217], v[12:15]
	v_mfma_f32_16x16x32_bf16 v[4:7], v[162:165], v[214:217], v[4:7]
	s_setprio 0
	s_setprio 1
	v_mfma_f32_16x16x32_bf16 v[56:59], v[166:169], v[186:189], v[56:59]
	v_mfma_f32_16x16x32_bf16 v[48:51], v[178:181], v[186:189], v[48:51]
	v_mfma_f32_16x16x32_bf16 v[40:43], v[166:169], v[194:197], v[40:43]
	v_mfma_f32_16x16x32_bf16 v[32:35], v[178:181], v[194:197], v[32:35]
	v_mfma_f32_16x16x32_bf16 v[24:27], v[166:169], v[202:205], v[24:27]
	v_mfma_f32_16x16x32_bf16 v[16:19], v[178:181], v[202:205], v[16:19]
	v_mfma_f32_16x16x32_bf16 v[8:11], v[166:169], v[210:213], v[8:11]
	v_mfma_f32_16x16x32_bf16 v[0:3], v[178:181], v[210:213], v[0:3]
	v_mfma_f32_16x16x32_bf16 v[56:59], v[170:173], v[190:193], v[56:59]
	v_mfma_f32_16x16x32_bf16 v[48:51], v[182:185], v[190:193], v[48:51]
	v_mfma_f32_16x16x32_bf16 v[40:43], v[170:173], v[198:201], v[40:43]
	v_mfma_f32_16x16x32_bf16 v[32:35], v[182:185], v[198:201], v[32:35]
	v_mfma_f32_16x16x32_bf16 v[24:27], v[170:173], v[206:209], v[24:27]
	v_mfma_f32_16x16x32_bf16 v[16:19], v[182:185], v[206:209], v[16:19]
	v_mfma_f32_16x16x32_bf16 v[8:11], v[170:173], v[214:217], v[8:11]
	v_mfma_f32_16x16x32_bf16 v[0:3], v[182:185], v[214:217], v[0:3]
	s_setprio 0
	s_barrier
	s_add_i32 s49, 0, 0x18000
	s_add_i32 s50, 0, 0x1c000
	v_add_u32_e32 v162, s49, v149
	v_add_u32_e32 v176, s50, v149
	ds_read_b128 v[144:147], v162
	ds_read_b128 v[154:157], v162 offset:1024
	ds_read_b128 v[158:161], v162 offset:2048
	ds_read_b128 v[162:165], v162 offset:3072
	ds_read_b128 v[166:169], v176
	ds_read_b128 v[170:173], v176 offset:1024
	ds_read_b128 v[178:181], v176 offset:2048
	ds_read_b128 v[182:185], v176 offset:3072
	s_add_u32 s28, s28, 0x40000
	s_addc_u32 s29, s29, 0
	s_mov_b32 m0, s35
	v_lshl_add_u64 v[224:225], s[28:29], 0, v[134:135]
	ds_read_b128 v[186:189], v153 offset:32768
	ds_read_b128 v[190:193], v153 offset:33792
	ds_read_b128 v[194:197], v153 offset:34816
	ds_read_b128 v[198:201], v153 offset:35840
	ds_read_b128 v[202:205], v153 offset:36864
	ds_read_b128 v[206:209], v153 offset:37888
	ds_read_b128 v[210:213], v153 offset:38912
	ds_read_b128 v[214:217], v153 offset:39936
	global_load_lds_dwordx4 v[224:225], off
	v_lshl_add_u64 v[224:225], s[28:29], 0, v[130:131]
	s_mov_b32 m0, s36
	s_nop 0
	global_load_lds_dwordx4 v[224:225], off
	s_waitcnt vmcnt(8)
	s_waitcnt lgkmcnt(0)
	s_barrier
	s_setprio 1
	s_waitcnt lgkmcnt(0)
	v_mfma_f32_16x16x32_bf16 v[124:127], v[144:147], v[186:189], v[124:127]
	v_mfma_f32_16x16x32_bf16 v[116:119], v[158:161], v[186:189], v[116:119]
	v_mfma_f32_16x16x32_bf16 v[108:111], v[144:147], v[194:197], v[108:111]
	v_mfma_f32_16x16x32_bf16 v[100:103], v[158:161], v[194:197], v[100:103]
	v_mfma_f32_16x16x32_bf16 v[92:95], v[144:147], v[202:205], v[92:95]
	v_mfma_f32_16x16x32_bf16 v[84:87], v[158:161], v[202:205], v[84:87]
	v_mfma_f32_16x16x32_bf16 v[76:79], v[144:147], v[210:213], v[76:79]
	v_mfma_f32_16x16x32_bf16 v[68:71], v[158:161], v[210:213], v[68:71]
	v_mfma_f32_16x16x32_bf16 v[124:127], v[154:157], v[190:193], v[124:127]
	v_mfma_f32_16x16x32_bf16 v[116:119], v[162:165], v[190:193], v[116:119]
	v_mfma_f32_16x16x32_bf16 v[108:111], v[154:157], v[198:201], v[108:111]
	v_mfma_f32_16x16x32_bf16 v[100:103], v[162:165], v[198:201], v[100:103]
	v_mfma_f32_16x16x32_bf16 v[92:95], v[154:157], v[206:209], v[92:95]
	v_mfma_f32_16x16x32_bf16 v[84:87], v[162:165], v[206:209], v[84:87]
	v_mfma_f32_16x16x32_bf16 v[76:79], v[154:157], v[214:217], v[76:79]
	v_mfma_f32_16x16x32_bf16 v[68:71], v[162:165], v[214:217], v[68:71]
	s_setprio 0
	s_setprio 1
	v_mfma_f32_16x16x32_bf16 v[120:123], v[166:169], v[186:189], v[120:123]
	v_mfma_f32_16x16x32_bf16 v[112:115], v[178:181], v[186:189], v[112:115]
	v_mfma_f32_16x16x32_bf16 v[104:107], v[166:169], v[194:197], v[104:107]
	v_mfma_f32_16x16x32_bf16 v[96:99], v[178:181], v[194:197], v[96:99]
	v_mfma_f32_16x16x32_bf16 v[88:91], v[166:169], v[202:205], v[88:91]
	v_mfma_f32_16x16x32_bf16 v[80:83], v[178:181], v[202:205], v[80:83]
	v_mfma_f32_16x16x32_bf16 v[72:75], v[166:169], v[210:213], v[72:75]
	v_mfma_f32_16x16x32_bf16 v[64:67], v[178:181], v[210:213], v[64:67]
	v_mfma_f32_16x16x32_bf16 v[120:123], v[170:173], v[190:193], v[120:123]
	v_mfma_f32_16x16x32_bf16 v[112:115], v[182:185], v[190:193], v[112:115]
	v_mfma_f32_16x16x32_bf16 v[104:107], v[170:173], v[198:201], v[104:107]
	v_mfma_f32_16x16x32_bf16 v[96:99], v[182:185], v[198:201], v[96:99]
	v_mfma_f32_16x16x32_bf16 v[88:91], v[170:173], v[206:209], v[88:91]
	v_mfma_f32_16x16x32_bf16 v[80:83], v[182:185], v[206:209], v[80:83]
	v_mfma_f32_16x16x32_bf16 v[72:75], v[170:173], v[214:217], v[72:75]
	v_mfma_f32_16x16x32_bf16 v[64:67], v[182:185], v[214:217], v[64:67]
	s_setprio 0
	s_barrier
	s_add_i32 s28, s49, s33
	v_lshl_add_u64 v[174:175], v[174:175], 0, s[10:11]
	s_mov_b32 m0, s28
	ds_read_b128 v[186:189], v153 offset:49152
	ds_read_b128 v[190:193], v153 offset:50176
	ds_read_b128 v[194:197], v153 offset:51200
	ds_read_b128 v[198:201], v153 offset:52224
	ds_read_b128 v[202:205], v153 offset:53248
	ds_read_b128 v[206:209], v153 offset:54272
	ds_read_b128 v[210:213], v153 offset:55296
	ds_read_b128 v[214:217], v153 offset:56320
	global_load_lds_dwordx4 v[174:175], off
	s_add_i32 m0, s28, 0x2000
	s_add_u32 s26, s26, 0x40080
	v_lshl_add_u64 v[174:175], v[218:219], 0, s[10:11]
	s_addc_u32 s27, s27, 0
	s_add_i32 s28, s50, s33
	global_load_lds_dwordx4 v[174:175], off
	v_lshl_add_u64 v[174:175], s[26:27], 0, v[132:133]
	s_mov_b32 m0, s28
	s_nop 0
	global_load_lds_dwordx4 v[174:175], off
	v_lshl_add_u64 v[174:175], s[26:27], 0, v[128:129]
	s_add_i32 m0, s28, 0x2000
	s_nop 0
	global_load_lds_dwordx4 v[174:175], off
	v_lshl_add_u64 v[174:175], v[220:221], 0, s[10:11]
	s_mov_b32 m0, s38
	s_nop 0
	global_load_lds_dwordx4 v[174:175], off
	v_lshl_add_u64 v[174:175], v[222:223], 0, s[10:11]
	s_mov_b32 m0, s39
	s_nop 0
	global_load_lds_dwordx4 v[174:175], off
	s_waitcnt vmcnt(8)
	s_waitcnt lgkmcnt(0)
	s_barrier
	s_setprio 1
	s_waitcnt lgkmcnt(0)
	v_mfma_f32_16x16x32_bf16 v[60:63], v[144:147], v[186:189], v[60:63]
	v_mfma_f32_16x16x32_bf16 v[52:55], v[158:161], v[186:189], v[52:55]
	v_mfma_f32_16x16x32_bf16 v[44:47], v[144:147], v[194:197], v[44:47]
	v_mfma_f32_16x16x32_bf16 v[36:39], v[158:161], v[194:197], v[36:39]
	v_mfma_f32_16x16x32_bf16 v[28:31], v[144:147], v[202:205], v[28:31]
	v_mfma_f32_16x16x32_bf16 v[20:23], v[158:161], v[202:205], v[20:23]
	v_mfma_f32_16x16x32_bf16 v[12:15], v[144:147], v[210:213], v[12:15]
	v_mfma_f32_16x16x32_bf16 v[4:7], v[158:161], v[210:213], v[4:7]
	v_mfma_f32_16x16x32_bf16 v[60:63], v[154:157], v[190:193], v[60:63]
	v_mfma_f32_16x16x32_bf16 v[52:55], v[162:165], v[190:193], v[52:55]
	v_mfma_f32_16x16x32_bf16 v[44:47], v[154:157], v[198:201], v[44:47]
	v_mfma_f32_16x16x32_bf16 v[36:39], v[162:165], v[198:201], v[36:39]
	v_mfma_f32_16x16x32_bf16 v[28:31], v[154:157], v[206:209], v[28:31]
	v_mfma_f32_16x16x32_bf16 v[20:23], v[162:165], v[206:209], v[20:23]
	v_mfma_f32_16x16x32_bf16 v[12:15], v[154:157], v[214:217], v[12:15]
	v_mfma_f32_16x16x32_bf16 v[4:7], v[162:165], v[214:217], v[4:7]
	s_setprio 0
	s_setprio 1
	v_mfma_f32_16x16x32_bf16 v[56:59], v[166:169], v[186:189], v[56:59]
	v_mfma_f32_16x16x32_bf16 v[48:51], v[178:181], v[186:189], v[48:51]
	v_mfma_f32_16x16x32_bf16 v[40:43], v[166:169], v[194:197], v[40:43]
	v_mfma_f32_16x16x32_bf16 v[32:35], v[178:181], v[194:197], v[32:35]
	v_mfma_f32_16x16x32_bf16 v[24:27], v[166:169], v[202:205], v[24:27]
	v_mfma_f32_16x16x32_bf16 v[16:19], v[178:181], v[202:205], v[16:19]
	v_mfma_f32_16x16x32_bf16 v[8:11], v[166:169], v[210:213], v[8:11]
	v_mfma_f32_16x16x32_bf16 v[0:3], v[178:181], v[210:213], v[0:3]
	v_mfma_f32_16x16x32_bf16 v[56:59], v[170:173], v[190:193], v[56:59]
	v_mfma_f32_16x16x32_bf16 v[48:51], v[182:185], v[190:193], v[48:51]
	v_mfma_f32_16x16x32_bf16 v[40:43], v[170:173], v[198:201], v[40:43]
	v_mfma_f32_16x16x32_bf16 v[32:35], v[182:185], v[198:201], v[32:35]
	v_mfma_f32_16x16x32_bf16 v[24:27], v[170:173], v[206:209], v[24:27]
	v_mfma_f32_16x16x32_bf16 v[16:19], v[182:185], v[206:209], v[16:19]
	v_mfma_f32_16x16x32_bf16 v[8:11], v[170:173], v[214:217], v[8:11]
	v_mfma_f32_16x16x32_bf16 v[0:3], v[182:185], v[214:217], v[0:3]
	s_setprio 0
	s_barrier
	s_add_i32 s48, s48, 2
	s_add_u32 s24, s24, 0x100
	s_addc_u32 s25, s25, 0
	s_add_u32 s46, s46, 0x100
	s_addc_u32 s47, s47, 0
	s_cmp_gt_u32 s48, 13
	s_cbranch_scc0 .LBB0_1152
	s_and_b64 vcc, exec, s[12:13]
	s_cbranch_vccz .LBB0_1155
	s_and_b64 vcc, exec, s[6:7]
	s_cbranch_vccnz .LBB0_1155
	s_barrier
.LBB0_1155:
	v_mul_f32_e32 v155, 0xbfb8aa3b, v124
	v_exp_f32_e32 v155, v155
	v_mul_f32_e32 v158, 0xbfb8aa3b, v125
	v_exp_f32_e32 v159, v158
	v_lshl_add_u32 v154, s22, 8, v148
	v_add_f32_e32 v155, 1.0, v155
	v_rcp_f32_e32 v158, v155
	v_add_f32_e32 v155, 1.0, v159
	v_mul_f32_e32 v159, 0xbfb8aa3b, v126
	v_exp_f32_e32 v160, v159
	v_mul_f32_e32 v159, 0xbfb8aa3b, v127
	v_exp_f32_e32 v161, v159
	v_rcp_f32_e32 v159, v155
	v_add_f32_e32 v155, 1.0, v160
	v_rcp_f32_e32 v160, v155
	v_add_f32_e32 v155, 1.0, v161
	v_rcp_f32_e32 v161, v155
	v_pk_mul_f32 v[124:125], v[124:125], v[158:159]
	v_lshl_or_b32 v144, s43, 7, v150
	v_pk_mul_f32 v[120:121], v[124:125], v[120:121]
	v_pk_mul_f32 v[124:125], v[126:127], v[160:161]
	v_cvt_pk_bf16_f32 v120, v120, v121
	v_mul_f32_e32 v121, 0xbfb8aa3b, v116
	v_pk_mul_f32 v[122:123], v[124:125], v[122:123]
	v_exp_f32_e32 v124, v121
	v_mul_f32_e32 v121, 0xbfb8aa3b, v117
	v_exp_f32_e32 v125, v121
	v_cvt_pk_bf16_f32 v121, v122, v123
	v_add_f32_e32 v122, 1.0, v124
	v_mul_f32_e32 v124, 0xbfb8aa3b, v118
	v_add_f32_e32 v123, 1.0, v125
	v_mul_f32_e32 v125, 0xbfb8aa3b, v119
	v_exp_f32_e32 v124, v124
	v_exp_f32_e32 v125, v125
	v_rcp_f32_e32 v122, v122
	v_rcp_f32_e32 v123, v123
	v_add_f32_e32 v124, 1.0, v124
	v_add_f32_e32 v125, 1.0, v125
	v_rcp_f32_e32 v124, v124
	v_rcp_f32_e32 v125, v125
	v_pk_mul_f32 v[116:117], v[116:117], v[122:123]
	v_ashrrev_i32_e32 v145, 31, v144
	v_pk_mul_f32 v[112:113], v[116:117], v[112:113]
	v_mul_f32_e32 v116, 0xbfb8aa3b, v110
	v_cvt_pk_bf16_f32 v122, v112, v113
	v_pk_mul_f32 v[112:113], v[118:119], v[124:125]
	v_mul_f32_e32 v117, 0xbfb8aa3b, v111
	v_pk_mul_f32 v[112:113], v[112:113], v[114:115]
	v_mul_f32_e32 v114, 0xbfb8aa3b, v108
	v_mul_f32_e32 v115, 0xbfb8aa3b, v109
	v_exp_f32_e32 v114, v114
	v_exp_f32_e32 v115, v115
	v_exp_f32_e32 v116, v116
	v_exp_f32_e32 v117, v117
	v_add_f32_e32 v114, 1.0, v114
	v_add_f32_e32 v115, 1.0, v115
	v_rcp_f32_e32 v114, v114
	v_rcp_f32_e32 v115, v115
	v_add_f32_e32 v116, 1.0, v116
	v_add_f32_e32 v117, 1.0, v117
	v_rcp_f32_e32 v116, v116
	v_rcp_f32_e32 v117, v117
	v_pk_mul_f32 v[108:109], v[108:109], v[114:115]
	v_mov_b64_e32 v[146:147], s[8:9]
	v_pk_mul_f32 v[104:105], v[108:109], v[104:105]
	v_pk_mul_f32 v[108:109], v[110:111], v[116:117]
	v_cvt_pk_bf16_f32 v104, v104, v105
	v_mul_f32_e32 v105, 0xbfb8aa3b, v100
	v_pk_mul_f32 v[106:107], v[108:109], v[106:107]
	v_exp_f32_e32 v108, v105
	v_mul_f32_e32 v105, 0xbfb8aa3b, v101
	v_exp_f32_e32 v109, v105
	v_cvt_pk_bf16_f32 v105, v106, v107
	v_add_f32_e32 v106, 1.0, v108
	v_mul_f32_e32 v108, 0xbfb8aa3b, v102
	v_add_f32_e32 v107, 1.0, v109
	v_mul_f32_e32 v109, 0xbfb8aa3b, v103
	v_exp_f32_e32 v108, v108
	v_exp_f32_e32 v109, v109
	v_rcp_f32_e32 v106, v106
	v_rcp_f32_e32 v107, v107
	v_add_f32_e32 v108, 1.0, v108
	v_add_f32_e32 v109, 1.0, v109
	v_rcp_f32_e32 v108, v108
	v_rcp_f32_e32 v109, v109
	v_pk_mul_f32 v[100:101], v[100:101], v[106:107]
	v_cvt_pk_bf16_f32 v123, v112, v113
	v_pk_mul_f32 v[96:97], v[100:101], v[96:97]
	v_mul_f32_e32 v100, 0xbfb8aa3b, v94
	v_cvt_pk_bf16_f32 v106, v96, v97
	v_pk_mul_f32 v[96:97], v[102:103], v[108:109]
	v_mul_f32_e32 v101, 0xbfb8aa3b, v95
	v_pk_mul_f32 v[96:97], v[96:97], v[98:99]
	v_mul_f32_e32 v98, 0xbfb8aa3b, v92
	v_mul_f32_e32 v99, 0xbfb8aa3b, v93
	v_exp_f32_e32 v98, v98
	v_exp_f32_e32 v99, v99
	v_exp_f32_e32 v100, v100
	v_exp_f32_e32 v101, v101
	v_add_f32_e32 v98, 1.0, v98
	v_add_f32_e32 v99, 1.0, v99
	v_rcp_f32_e32 v98, v98
	v_rcp_f32_e32 v99, v99
	v_add_f32_e32 v100, 1.0, v100
	v_add_f32_e32 v101, 1.0, v101
	v_rcp_f32_e32 v100, v100
	v_rcp_f32_e32 v101, v101
	v_pk_mul_f32 v[92:93], v[92:93], v[98:99]
	v_or_b32_e32 v112, 16, v154
	v_pk_mul_f32 v[88:89], v[92:93], v[88:89]
	v_pk_mul_f32 v[92:93], v[94:95], v[100:101]
	v_cvt_pk_bf16_f32 v88, v88, v89
	v_mul_f32_e32 v89, 0xbfb8aa3b, v84
	v_pk_mul_f32 v[90:91], v[92:93], v[90:91]
	v_exp_f32_e32 v92, v89
	v_mul_f32_e32 v89, 0xbfb8aa3b, v85
	v_exp_f32_e32 v93, v89
	v_cvt_pk_bf16_f32 v89, v90, v91
	v_add_f32_e32 v90, 1.0, v92
	v_mul_f32_e32 v92, 0xbfb8aa3b, v86
	v_add_f32_e32 v91, 1.0, v93
	v_mul_f32_e32 v93, 0xbfb8aa3b, v87
	v_exp_f32_e32 v92, v92
	v_exp_f32_e32 v93, v93
	v_rcp_f32_e32 v90, v90
	v_rcp_f32_e32 v91, v91
	v_add_f32_e32 v92, 1.0, v92
	v_add_f32_e32 v93, 1.0, v93
	v_rcp_f32_e32 v92, v92
	v_rcp_f32_e32 v93, v93
	v_pk_mul_f32 v[84:85], v[84:85], v[90:91]
	v_cvt_pk_bf16_f32 v107, v96, v97
	v_pk_mul_f32 v[80:81], v[84:85], v[80:81]
	v_mul_f32_e32 v84, 0xbfb8aa3b, v78
	v_cvt_pk_bf16_f32 v90, v80, v81
	v_pk_mul_f32 v[80:81], v[86:87], v[92:93]
	v_mul_f32_e32 v85, 0xbfb8aa3b, v79
	v_pk_mul_f32 v[80:81], v[80:81], v[82:83]
	v_mul_f32_e32 v82, 0xbfb8aa3b, v76
	v_mul_f32_e32 v83, 0xbfb8aa3b, v77
	v_exp_f32_e32 v82, v82
	v_exp_f32_e32 v83, v83
	v_exp_f32_e32 v84, v84
	v_exp_f32_e32 v85, v85
	v_add_f32_e32 v82, 1.0, v82
	v_add_f32_e32 v83, 1.0, v83
	v_rcp_f32_e32 v82, v82
	v_rcp_f32_e32 v83, v83
	v_add_f32_e32 v84, 1.0, v84
	v_add_f32_e32 v85, 1.0, v85
	v_rcp_f32_e32 v84, v84
	v_rcp_f32_e32 v85, v85
	v_pk_mul_f32 v[76:77], v[76:77], v[82:83]
	v_or_b32_e32 v96, 32, v154
	v_pk_mul_f32 v[72:73], v[76:77], v[72:73]
	v_pk_mul_f32 v[76:77], v[78:79], v[84:85]
	v_cvt_pk_bf16_f32 v72, v72, v73
	v_mul_f32_e32 v73, 0xbfb8aa3b, v68
	v_pk_mul_f32 v[74:75], v[76:77], v[74:75]
	v_exp_f32_e32 v76, v73
	v_mul_f32_e32 v73, 0xbfb8aa3b, v69
	v_exp_f32_e32 v77, v73
	v_cvt_pk_bf16_f32 v73, v74, v75
	v_add_f32_e32 v74, 1.0, v76
	v_mul_f32_e32 v76, 0xbfb8aa3b, v70
	v_add_f32_e32 v75, 1.0, v77
	v_mul_f32_e32 v77, 0xbfb8aa3b, v71
	v_exp_f32_e32 v76, v76
	v_exp_f32_e32 v77, v77
	v_rcp_f32_e32 v74, v74
	v_rcp_f32_e32 v75, v75
	v_add_f32_e32 v76, 1.0, v76
	v_add_f32_e32 v77, 1.0, v77
	v_rcp_f32_e32 v76, v76
	v_rcp_f32_e32 v77, v77
	v_pk_mul_f32 v[68:69], v[68:69], v[74:75]
	v_cvt_pk_bf16_f32 v91, v80, v81
	v_pk_mul_f32 v[64:65], v[68:69], v[64:65]
	v_mul_f32_e32 v68, 0xbfb8aa3b, v62
	v_cvt_pk_bf16_f32 v74, v64, v65
	v_pk_mul_f32 v[64:65], v[70:71], v[76:77]
	v_mul_f32_e32 v69, 0xbfb8aa3b, v63
	v_pk_mul_f32 v[64:65], v[64:65], v[66:67]
	v_mul_f32_e32 v66, 0xbfb8aa3b, v60
	v_mul_f32_e32 v67, 0xbfb8aa3b, v61
	v_exp_f32_e32 v66, v66
	v_exp_f32_e32 v67, v67
	v_exp_f32_e32 v68, v68
	v_exp_f32_e32 v69, v69
	v_add_f32_e32 v66, 1.0, v66
	v_add_f32_e32 v67, 1.0, v67
	v_rcp_f32_e32 v66, v66
	v_rcp_f32_e32 v67, v67
	v_add_f32_e32 v68, 1.0, v68
	v_add_f32_e32 v69, 1.0, v69
	v_rcp_f32_e32 v68, v68
	v_rcp_f32_e32 v69, v69
	v_pk_mul_f32 v[60:61], v[60:61], v[66:67]
	v_or_b32_e32 v80, 48, v154
	v_pk_mul_f32 v[56:57], v[60:61], v[56:57]
	v_pk_mul_f32 v[60:61], v[62:63], v[68:69]
	v_cvt_pk_bf16_f32 v56, v56, v57
	v_mul_f32_e32 v57, 0xbfb8aa3b, v52
	v_pk_mul_f32 v[58:59], v[60:61], v[58:59]
	v_exp_f32_e32 v60, v57
	v_mul_f32_e32 v57, 0xbfb8aa3b, v53
	v_exp_f32_e32 v61, v57
	v_cvt_pk_bf16_f32 v57, v58, v59
	v_add_f32_e32 v58, 1.0, v60
	v_mul_f32_e32 v60, 0xbfb8aa3b, v54
	v_add_f32_e32 v59, 1.0, v61
	v_mul_f32_e32 v61, 0xbfb8aa3b, v55
	v_exp_f32_e32 v60, v60
	v_exp_f32_e32 v61, v61
	v_rcp_f32_e32 v58, v58
	v_rcp_f32_e32 v59, v59
	v_add_f32_e32 v60, 1.0, v60
	v_add_f32_e32 v61, 1.0, v61
	v_rcp_f32_e32 v60, v60
	v_rcp_f32_e32 v61, v61
	v_pk_mul_f32 v[52:53], v[52:53], v[58:59]
	v_cvt_pk_bf16_f32 v75, v64, v65
	v_pk_mul_f32 v[48:49], v[52:53], v[48:49]
	v_mul_f32_e32 v52, 0xbfb8aa3b, v46
	v_cvt_pk_bf16_f32 v58, v48, v49
	v_pk_mul_f32 v[48:49], v[54:55], v[60:61]
	v_mul_f32_e32 v53, 0xbfb8aa3b, v47
	v_pk_mul_f32 v[48:49], v[48:49], v[50:51]
	v_mul_f32_e32 v50, 0xbfb8aa3b, v44
	v_mul_f32_e32 v51, 0xbfb8aa3b, v45
	v_exp_f32_e32 v50, v50
	v_exp_f32_e32 v51, v51
	v_exp_f32_e32 v52, v52
	v_exp_f32_e32 v53, v53
	v_add_f32_e32 v50, 1.0, v50
	v_add_f32_e32 v51, 1.0, v51
	v_rcp_f32_e32 v50, v50
	v_rcp_f32_e32 v51, v51
	v_add_f32_e32 v52, 1.0, v52
	v_add_f32_e32 v53, 1.0, v53
	v_rcp_f32_e32 v52, v52
	v_rcp_f32_e32 v53, v53
	v_pk_mul_f32 v[44:45], v[44:45], v[50:51]
	v_add_u32_e32 v64, 0x80, v154
	v_pk_mul_f32 v[40:41], v[44:45], v[40:41]
	v_pk_mul_f32 v[44:45], v[46:47], v[52:53]
	v_cvt_pk_bf16_f32 v40, v40, v41
	v_mul_f32_e32 v41, 0xbfb8aa3b, v36
	v_pk_mul_f32 v[42:43], v[44:45], v[42:43]
	v_exp_f32_e32 v44, v41
	v_mul_f32_e32 v41, 0xbfb8aa3b, v37
	v_exp_f32_e32 v45, v41
	v_cvt_pk_bf16_f32 v41, v42, v43
	v_add_f32_e32 v42, 1.0, v44
	v_mul_f32_e32 v44, 0xbfb8aa3b, v38
	v_add_f32_e32 v43, 1.0, v45
	v_mul_f32_e32 v45, 0xbfb8aa3b, v39
	v_exp_f32_e32 v44, v44
	v_exp_f32_e32 v45, v45
	v_rcp_f32_e32 v42, v42
	v_rcp_f32_e32 v43, v43
	v_add_f32_e32 v44, 1.0, v44
	v_add_f32_e32 v45, 1.0, v45
	v_rcp_f32_e32 v44, v44
	v_rcp_f32_e32 v45, v45
	v_pk_mul_f32 v[36:37], v[36:37], v[42:43]
	v_cvt_pk_bf16_f32 v59, v48, v49
	v_pk_mul_f32 v[32:33], v[36:37], v[32:33]
	v_mul_f32_e32 v36, 0xbfb8aa3b, v30
	v_cvt_pk_bf16_f32 v42, v32, v33
	v_pk_mul_f32 v[32:33], v[38:39], v[44:45]
	v_mul_f32_e32 v37, 0xbfb8aa3b, v31
	v_pk_mul_f32 v[32:33], v[32:33], v[34:35]
	v_mul_f32_e32 v34, 0xbfb8aa3b, v28
	v_mul_f32_e32 v35, 0xbfb8aa3b, v29
	v_exp_f32_e32 v34, v34
	v_exp_f32_e32 v35, v35
	v_exp_f32_e32 v36, v36
	v_exp_f32_e32 v37, v37
	v_add_f32_e32 v34, 1.0, v34
	v_add_f32_e32 v35, 1.0, v35
	v_rcp_f32_e32 v34, v34
	v_rcp_f32_e32 v35, v35
	v_add_f32_e32 v36, 1.0, v36
	v_add_f32_e32 v37, 1.0, v37
	v_rcp_f32_e32 v36, v36
	v_rcp_f32_e32 v37, v37
	v_pk_mul_f32 v[28:29], v[28:29], v[34:35]
	v_add_u32_e32 v48, 0x90, v154
	v_pk_mul_f32 v[24:25], v[28:29], v[24:25]
	v_pk_mul_f32 v[28:29], v[30:31], v[36:37]
	v_cvt_pk_bf16_f32 v24, v24, v25
	v_mul_f32_e32 v25, 0xbfb8aa3b, v20
	v_pk_mul_f32 v[26:27], v[28:29], v[26:27]
	v_exp_f32_e32 v28, v25
	v_mul_f32_e32 v25, 0xbfb8aa3b, v21
	v_exp_f32_e32 v29, v25
	v_cvt_pk_bf16_f32 v25, v26, v27
	v_add_f32_e32 v26, 1.0, v28
	v_mul_f32_e32 v28, 0xbfb8aa3b, v22
	v_add_f32_e32 v27, 1.0, v29
	v_mul_f32_e32 v29, 0xbfb8aa3b, v23
	v_exp_f32_e32 v28, v28
	v_exp_f32_e32 v29, v29
	v_rcp_f32_e32 v26, v26
	v_rcp_f32_e32 v27, v27
	v_add_f32_e32 v28, 1.0, v28
	v_add_f32_e32 v29, 1.0, v29
	v_rcp_f32_e32 v28, v28
	v_rcp_f32_e32 v29, v29
	v_pk_mul_f32 v[20:21], v[20:21], v[26:27]
	v_cvt_pk_bf16_f32 v43, v32, v33
	v_pk_mul_f32 v[16:17], v[20:21], v[16:17]
	v_mul_f32_e32 v20, 0xbfb8aa3b, v14
	v_cvt_pk_bf16_f32 v26, v16, v17
	v_pk_mul_f32 v[16:17], v[22:23], v[28:29]
	v_mul_f32_e32 v21, 0xbfb8aa3b, v15
	v_pk_mul_f32 v[16:17], v[16:17], v[18:19]
	v_mul_f32_e32 v18, 0xbfb8aa3b, v12
	v_mul_f32_e32 v19, 0xbfb8aa3b, v13
	v_exp_f32_e32 v18, v18
	v_exp_f32_e32 v19, v19
	v_exp_f32_e32 v20, v20
	v_exp_f32_e32 v21, v21
	v_add_f32_e32 v18, 1.0, v18
	v_add_f32_e32 v19, 1.0, v19
	v_rcp_f32_e32 v18, v18
	v_rcp_f32_e32 v19, v19
	v_add_f32_e32 v20, 1.0, v20
	v_add_f32_e32 v21, 1.0, v21
	v_rcp_f32_e32 v20, v20
	v_rcp_f32_e32 v21, v21
	v_pk_mul_f32 v[12:13], v[12:13], v[18:19]
	v_add_u32_e32 v32, 0xa0, v154
	v_pk_mul_f32 v[8:9], v[12:13], v[8:9]
	v_pk_mul_f32 v[12:13], v[14:15], v[20:21]
	v_cvt_pk_bf16_f32 v8, v8, v9
	v_mul_f32_e32 v9, 0xbfb8aa3b, v4
	v_pk_mul_f32 v[10:11], v[12:13], v[10:11]
	v_exp_f32_e32 v12, v9
	v_mul_f32_e32 v9, 0xbfb8aa3b, v5
	v_exp_f32_e32 v13, v9
	v_cvt_pk_bf16_f32 v9, v10, v11
	v_add_f32_e32 v10, 1.0, v12
	v_mul_f32_e32 v12, 0xbfb8aa3b, v6
	v_add_f32_e32 v11, 1.0, v13
	v_mul_f32_e32 v13, 0xbfb8aa3b, v7
	v_exp_f32_e32 v12, v12
	v_exp_f32_e32 v13, v13
	v_rcp_f32_e32 v10, v10
	v_rcp_f32_e32 v11, v11
	v_add_f32_e32 v12, 1.0, v12
	v_add_f32_e32 v13, 1.0, v13
	v_rcp_f32_e32 v12, v12
	v_rcp_f32_e32 v13, v13
	v_pk_mul_f32 v[4:5], v[4:5], v[10:11]
	v_cvt_pk_bf16_f32 v27, v16, v17
	v_pk_mul_f32 v[0:1], v[4:5], v[0:1]
	v_add_u32_e32 v16, 0xb0, v154
	v_cvt_pk_bf16_f32 v10, v0, v1
	v_pk_mul_f32 v[0:1], v[6:7], v[12:13]
	v_mad_i64_i32 v[156:157], s[24:25], v154, s42, v[146:147]
	v_lshlrev_b64 v[144:145], 1, v[144:145]
	v_mad_i64_i32 v[112:113], s[24:25], v112, s42, v[146:147]
	v_mad_i64_i32 v[96:97], s[24:25], v96, s42, v[146:147]
	v_mad_i64_i32 v[80:81], s[24:25], v80, s42, v[146:147]
	v_mad_i64_i32 v[64:65], s[24:25], v64, s42, v[146:147]
	v_mad_i64_i32 v[48:49], s[24:25], v48, s42, v[146:147]
	v_mad_i64_i32 v[32:33], s[24:25], v32, s42, v[146:147]
	v_mad_i64_i32 v[16:17], s[24:25], v16, s42, v[146:147]
	v_pk_mul_f32 v[0:1], v[0:1], v[2:3]
	v_lshl_add_u64 v[156:157], v[156:157], 0, v[144:145]
	v_lshl_add_u64 v[112:113], v[112:113], 0, v[144:145]
	v_lshl_add_u64 v[96:97], v[96:97], 0, v[144:145]
	v_lshl_add_u64 v[80:81], v[80:81], 0, v[144:145]
	v_lshl_add_u64 v[64:65], v[64:65], 0, v[144:145]
	v_lshl_add_u64 v[48:49], v[48:49], 0, v[144:145]
	v_lshl_add_u64 v[32:33], v[32:33], 0, v[144:145]
	v_lshl_add_u64 v[16:17], v[16:17], 0, v[144:145]
	v_cvt_pk_bf16_f32 v11, v0, v1
	s_andn2_b64 vcc, exec, s[6:7]
	s_mov_b64 s[6:7], -1
	global_store_dwordx4 v[156:157], v[120:123], off
	global_store_dwordx4 v[112:113], v[104:107], off
	global_store_dwordx4 v[96:97], v[88:91], off
	global_store_dwordx4 v[80:81], v[72:75], off
	global_store_dwordx4 v[64:65], v[56:59], off
	global_store_dwordx4 v[48:49], v[40:43], off
	global_store_dwordx4 v[32:33], v[24:27], off
	global_store_dwordx4 v[16:17], v[8:11], off
	s_cbranch_vccnz .LBB0_1144
	s_andn2_b64 vcc, exec, s[4:5]
	s_cbranch_vccnz .LBB0_1143
	s_branch .LBB0_1143
